# P5: sample-chain state loads hoisted (32 loads issued together, counted waits) and marked nt; prompt v loads nt (keeps shared q/k/T lines in L2)
# speedup vs baseline: 1.0014x; 1.0014x over previous
.LBB0_1982:
	v_readfirstlane_b32 s56, v37
	s_lshr_b32 s13, s56, 6
	s_lshl_b32 s12, s13, 4
	v_or_b32_e32 v52, s12, v36
	s_and_b64 vcc, exec, s[10:11]
	v_lshl_add_u64 v[2:3], s[60:61], 0, v[46:47]
	v_mov_b32_e32 v54, 0
	v_mov_b32_e32 v55, 0
	v_mov_b32_e32 v56, 0
	v_mov_b32_e32 v57, 0
	v_mov_b32_e32 v60, 0
	v_mov_b32_e32 v61, 0
	v_mov_b32_e32 v64, 0
	v_mov_b32_e32 v65, 0
	v_mov_b32_e32 v58, 0
	v_mov_b32_e32 v59, 0
	v_mov_b32_e32 v68, 0
	v_mov_b32_e32 v69, 0
	v_mov_b32_e32 v66, 0
	v_mov_b32_e32 v67, 0
	v_mov_b32_e32 v74, 0
	v_mov_b32_e32 v75, 0
	v_mov_b32_e32 v62, 0
	v_mov_b32_e32 v63, 0
	v_mov_b32_e32 v70, 0
	v_mov_b32_e32 v71, 0
	v_mov_b32_e32 v76, 0
	v_mov_b32_e32 v77, 0
	v_mov_b32_e32 v78, 0
	v_mov_b32_e32 v79, 0
	v_mov_b32_e32 v72, 0
	v_mov_b32_e32 v73, 0
	v_mov_b32_e32 v80, 0
	v_mov_b32_e32 v81, 0
	v_mov_b32_e32 v82, 0
	v_mov_b32_e32 v83, 0
	v_mov_b32_e32 v84, 0
	v_mov_b32_e32 v85, 0
	s_cbranch_vccnz .Ls0_skip
	v_mov_b32_e32 v53, v35
	v_lshlrev_b64 v[4:5], 9, v[52:53]
	v_lshl_add_u64 v[4:5], v[2:3], 0, v[4:5]
	global_load_dword v54, v[4:5], off nt
	global_load_dword v55, v[4:5], off offset:512 nt
	global_load_dword v56, v[4:5], off offset:1024 nt
	global_load_dword v57, v[4:5], off offset:1536 nt
	global_load_dword v60, v[4:5], off offset:64 nt
	global_load_dword v61, v[4:5], off offset:576 nt
	global_load_dword v64, v[4:5], off offset:1088 nt
	global_load_dword v65, v[4:5], off offset:1600 nt
	global_load_dword v58, v[4:5], off offset:128 nt
	global_load_dword v59, v[4:5], off offset:640 nt
	global_load_dword v68, v[4:5], off offset:1152 nt
	global_load_dword v69, v[4:5], off offset:1664 nt
	global_load_dword v66, v[4:5], off offset:192 nt
	global_load_dword v67, v[4:5], off offset:704 nt
	global_load_dword v74, v[4:5], off offset:1216 nt
	global_load_dword v75, v[4:5], off offset:1728 nt
	global_load_dword v62, v[4:5], off offset:256 nt
	global_load_dword v63, v[4:5], off offset:768 nt
	global_load_dword v70, v[4:5], off offset:1280 nt
	global_load_dword v71, v[4:5], off offset:1792 nt
	global_load_dword v76, v[4:5], off offset:320 nt
	global_load_dword v77, v[4:5], off offset:832 nt
	global_load_dword v78, v[4:5], off offset:1344 nt
	global_load_dword v79, v[4:5], off offset:1856 nt
	global_load_dword v72, v[4:5], off offset:384 nt
	global_load_dword v73, v[4:5], off offset:896 nt
	global_load_dword v80, v[4:5], off offset:1408 nt
	global_load_dword v81, v[4:5], off offset:1920 nt
	global_load_dword v82, v[4:5], off offset:448 nt
	global_load_dword v83, v[4:5], off offset:960 nt
	global_load_dword v84, v[4:5], off offset:1472 nt
	global_load_dword v85, v[4:5], off offset:1984 nt
.Ls0_skip:
	s_lshl_b32 s86, s13, 5
	v_add_u32_e32 v6, s86, v39
	v_add_u32_e32 v103, v6, v87
	s_waitcnt vmcnt(28)
	v_cvt_pk_bf16_f32 v4, v54, v55
	v_cvt_pk_bf16_f32 v5, v56, v57
	ds_write_b64 v103, v[4:5]
	s_waitcnt vmcnt(24)
	v_cvt_pk_bf16_f32 v4, v60, v61
	v_cvt_pk_bf16_f32 v5, v64, v65
	ds_write_b64 v103, v[4:5] offset:4352
	s_waitcnt vmcnt(20)
	v_cvt_pk_bf16_f32 v4, v58, v59
	v_cvt_pk_bf16_f32 v5, v68, v69
	ds_write_b64 v103, v[4:5] offset:8704
	s_waitcnt vmcnt(16)
	v_cvt_pk_bf16_f32 v4, v66, v67
	v_cvt_pk_bf16_f32 v5, v74, v75
	ds_write_b64 v103, v[4:5] offset:13056
	s_waitcnt vmcnt(12)
	v_cvt_pk_bf16_f32 v4, v62, v63
	v_cvt_pk_bf16_f32 v5, v70, v71
	ds_write_b64 v103, v[4:5] offset:17408
	s_waitcnt vmcnt(8)
	v_cvt_pk_bf16_f32 v4, v76, v77
	v_cvt_pk_bf16_f32 v5, v78, v79
	ds_write_b64 v103, v[4:5] offset:21760
	s_waitcnt vmcnt(4)
	v_cvt_pk_bf16_f32 v4, v72, v73
	v_cvt_pk_bf16_f32 v5, v80, v81
	ds_write_b64 v103, v[4:5] offset:26112

.LBB0_2534:
	s_or_b64 exec, exec, s[6:7]
	s_and_b32 s35, s2, 63
	s_add_u32 s6, s64, s4
	s_addc_u32 s7, s65, 0
	v_mov_b32_e32 v2, 0
	v_mov_b32_e32 v97, v2
	s_add_u32 s5, s14, s4
	v_lshl_add_u64 v[98:99], s[6:7], 0, v[96:97]
	s_addc_u32 s12, s15, 0
	s_lshl_b64 s[6:7], s[8:9], 1
	s_add_u32 s6, s5, s6
	s_addc_u32 s7, s12, s7
	s_add_u32 s12, s6, s10
	s_addc_u32 s13, s7, 0
	v_lshlrev_b32_e32 v5, 4, v14
	v_lshlrev_b32_e32 v14, 1, v95
	v_mov_b32_e32 v15, v2
	s_add_u32 s4, s20, s4
	v_lshl_add_u64 v[100:101], s[12:13], 0, v[14:15]
	s_addc_u32 s5, s21, 0
	s_add_i32 s18, 0, 0x11400
	s_lshl_b32 s12, s38, 5
	s_add_u32 s12, s28, s12
	s_addc_u32 s13, s29, 0
	v_mov_b32_e32 v11, v2
	s_add_u32 s12, s12, 0xf191400
	v_or_b32_e32 v16, s16, v1
	v_or_b32_e32 v17, s16, v95
	v_lshl_add_u64 v[102:103], s[4:5], 0, v[10:11]
	v_lshlrev_b32_e32 v10, 4, v13
	s_addc_u32 s13, s13, 0
	v_lshl_add_u64 v[104:105], s[6:7], 0, v[14:15]
	s_add_i32 s6, 0, 0x15c00
	s_movk_i32 s7, 0x90
	v_add_u32_e32 v18, s18, v10
	v_add_u32_e32 v14, s6, v10
	v_mul_lo_u32 v10, v17, s7
	v_lshlrev_b32_e32 v11, 1, v117
	v_mul_lo_u32 v125, v16, s7
	s_movk_i32 s7, 0x48
	v_add3_u32 v123, 0, v10, v11
	v_mul_lo_u32 v10, v17, s7
	v_add_lshl_u32 v10, v10, v117, 1
	v_add_u32_e32 v11, 0x90, v10
	v_add_u32_e32 v128, s18, v11
	v_add_u32_e32 v129, s6, v11
	v_add_u32_e32 v11, 0x120, v10
	v_add_u32_e32 v130, s18, v11
	v_add_u32_e32 v131, s6, v11
	v_add_u32_e32 v11, 0x1b0, v10
	v_add_u32_e32 v132, s18, v11
	v_add_u32_e32 v133, s6, v11
	v_add_u32_e32 v11, 0x900, v10
	v_add_u32_e32 v134, s18, v11
	v_add_u32_e32 v135, s6, v11
	v_add_u32_e32 v11, 0x990, v10
	v_add_u32_e32 v126, s18, v10
	v_add_u32_e32 v127, s6, v10
	v_add_u32_e32 v136, s18, v11
	v_add_u32_e32 v137, s6, v11
	v_add_u32_e32 v11, 0xa20, v10
	v_add_u32_e32 v10, 0xab0, v10
	v_add_u32_e32 v139, s6, v11
	v_add_u32_e32 v141, s6, v10
	s_add_i32 s6, s16, s8
	s_ashr_i32 s16, s6, 4
	s_add_i32 s6, s6, 16
	s_add_i32 s44, s44, s38
	v_add_u32_e32 v138, s18, v11
	v_add_u32_e32 v140, s18, v10
	s_ashr_i32 s18, s6, 4
	s_lshl_b32 s6, s44, 14
	s_mul_i32 s40, s40, 0x8400
	s_add_i32 s38, s6, 0x20000
	s_or_b32 s6, s41, s40
	v_add_lshl_u32 v10, s6, v116, 2
	v_mov_b32_e32 v11, v2
	s_movk_i32 s17, 0x110
	v_lshl_add_u64 v[10:11], s[28:29], 0, v[10:11]
	s_mov_b64 s[6:7], 0xf006400
	s_lshr_b32 s45, s44, 3
	v_or_b32_e32 v119, 32, v94
	s_mov_b32 s11, 0
	v_lshl_add_u32 v122, v94, 1, 0
	v_mul_lo_u32 v15, v16, s17
	v_mul_u32_u24_e32 v16, 0x90, v1
	v_lshl_add_u64 v[106:107], v[10:11], 0, s[6:7]
	s_lshl_b32 s6, s45, 6
	v_add_u32_e32 v148, v12, v4
	v_mbcnt_lo_u32_b32 v4, -1, 0
	v_mul_u32_u24_e32 v120, 0x110, v118
	v_mul_u32_u24_e32 v121, 0x110, v117
	v_cmp_eq_u32_e64 s[4:5], 0, v13
	v_add_u32_e32 v124, 0x900, v123
	s_ashr_i32 s17, s16, 31
	s_ashr_i32 s19, s18, 31
	v_mul_u32_u24_e32 v142, 0x880, v13
	v_mul_u32_u24_e32 v143, 0x110, v119
	s_mov_b32 s39, s11
	s_sub_i32 s46, s6, 64
	s_sub_i32 s47, 0, s45
	v_lshlrev_b32_e32 v144, 1, v5
	v_add_u32_e32 v145, v122, v15
	v_add_u32_e32 v146, v18, v125
	s_mov_b32 s48, 0x5040100
	v_add_u32_e32 v147, v14, v16
	s_mov_b64 s[40:41], 0x1000
	v_mbcnt_hi_u32_b32 v149, -1, v4
	s_mov_b32 s49, s44
	s_mov_b32 s50, s11
	s_mov_b32 s51, s11
	v_mov_b32_e32 v22, 0
	v_mov_b32_e32 v23, v2
	v_mov_b32_e32 v24, v2
	v_mov_b32_e32 v25, v2
	v_mov_b32_e32 v18, 0
	v_mov_b32_e32 v19, v2
	v_mov_b32_e32 v20, v2
	v_mov_b32_e32 v21, v2
	v_mov_b32_e32 v14, 0
	v_mov_b32_e32 v15, v2
	v_mov_b32_e32 v16, v2
	v_mov_b32_e32 v17, v2
	v_mov_b32_e32 v10, 0
	v_mov_b32_e32 v11, v2
	v_mov_b32_e32 v12, v2
	v_mov_b32_e32 v13, v2
	v_and_b32_e32 v222, 7, v116
	v_lshlrev_b32_e32 v223, 4, v222
	v_lshlrev_b32_e32 v225, 5, v222
	v_add_u32_e32 v204, v120, v225
	v_add_u32_e32 v205, v121, v96
	v_mul_u32_u24_e32 v216, 0x90, v118
	v_add_u32_e32 v216, v216, v223
	v_add_u32_e32 v217, 0x13800, v216
	v_add_u32_e32 v218, 0x18000, v216
	v_mul_u32_u24_e32 v219, 0x90, v117
	v_add_u32_e32 v221, v219, v94
	v_add_u32_e32 v221, s10, v221
	v_add_u32_e32 v221, 0x18000, v221
	v_add_u32_e32 v219, v219, v96
	v_add_u32_e32 v220, 0x13800, v219
	s_and_b32 s66, s2, 7
	s_bfe_u32 s67, s2, 0x30003
	s_lshl_b32 s68, s66, 8
	s_and_b32 s69, s2, 64
	s_lshl_b32 s69, s69, 1
	v_lshlrev_b32_e32 v224, 11, v118
	v_add_u32_e32 v224, s68, v224
	v_mov_b32_e32 v227, 0
	v_mov_b32_e32 v229, 0
	v_add_u32_e32 v226, v224, v225
	v_add_u32_e32 v228, v224, v223
	v_add_u32_e32 v228, s69, v228
	s_lshl_b32 s70, s67, 4
	s_add_i32 s70, s70, 0x4400
	s_lshl_b32 s70, s70, 11
	s_add_u32 s36, s20, s70
	s_addc_u32 s37, s21, 0
	v_lshl_add_u64 v[206:207], s[36:37], 0, v[226:227]
	s_add_u32 s36, s64, s70
	s_addc_u32 s37, s65, 0
	v_lshl_add_u64 v[208:209], s[36:37], 0, v[226:227]
	s_add_u32 s36, s14, s70
	s_addc_u32 s37, s15, 0
	v_lshl_add_u64 v[210:211], s[36:37], 0, v[228:229]
	s_mul_i32 s70, s67, 0x108
	s_add_i32 s70, s70, s66
	s_lshl_b32 s71, s70, 14
	s_add_u32 s36, s62, s71
	s_addc_u32 s37, s63, 0
	v_lshlrev_b32_e32 v230, 4, v116
	v_mov_b32_e32 v231, 0
	v_lshl_add_u64 v[212:213], s[36:37], 0, v[230:231]
	v_add_u32_e32 v230, 0x2000, v230
	v_lshl_add_u64 v[214:215], s[36:37], 0, v[230:231]
	v_mov_b32_e32 v38, 0
	v_mov_b32_e32 v39, 0
	v_mov_b64_e32 v[40:41], v[38:39]
	v_mov_b64_e32 v[42:43], v[38:39]
	v_mov_b64_e32 v[44:45], v[38:39]
	v_mov_b64_e32 v[62:63], v[38:39]
	v_mov_b64_e32 v[64:65], v[38:39]
	v_mov_b64_e32 v[66:67], v[38:39]
	v_mov_b64_e32 v[68:69], v[38:39]
	v_mov_b64_e32 v[78:79], v[38:39]
	v_mov_b64_e32 v[80:81], v[38:39]
	v_cmp_gt_u32_e32 vcc, 16, v118
	s_and_saveexec_b64 s[70:71], vcc
	global_load_dwordx4 v[42:45], v[206:207], off
	global_load_dwordx4 v[38:41], v[206:207], off offset:16
	global_load_dwordx4 v[62:65], v[208:209], off
	global_load_dwordx4 v[66:69], v[208:209], off offset:16
	global_load_dwordx4 v[78:81], v[210:211], off nt
	s_or_b64 exec, exec, s[70:71]
	global_load_dwordx4 v[70:73], v[212:213], off
	global_load_dwordx4 v[74:77], v[214:215], off
	s_lshl_b32 s70, s67, 22
	s_add_u32 s36, s20, s70
	s_addc_u32 s37, s21, 0
	v_lshl_add_u64 v[206:207], s[36:37], 0, v[226:227]
	s_add_u32 s36, s64, s70
	s_addc_u32 s37, s65, 0
	v_lshl_add_u64 v[208:209], s[36:37], 0, v[226:227]
	s_add_u32 s36, s14, s70
	s_addc_u32 s37, s15, 0
	v_lshl_add_u64 v[210:211], s[36:37], 0, v[228:229]
	s_mov_b32 s36, 0x20000
	s_mov_b32 s37, 0
	v_lshl_add_u64 v[212:213], v[212:213], 0, s[36:37]
	v_lshl_add_u64 v[214:215], v[214:215], 0, s[36:37]
	s_waitcnt vmcnt(0)
	s_branch .LBB0_2537

.LBB0_2540:
	s_and_b32 s6, s51, 1
	s_mul_i32 s7, s6, 0x12000
	s_mulk_i32 s6, 0x4800
	s_add_i32 s55, s6, 0
	s_add_i32 s52, s7, 0
	s_add_i32 s55, s55, 0x1a400
	v_add3_u32 v4, s52, v120, v144
	s_waitcnt vmcnt(4)
	ds_write_b128 v4, v[42:45] offset:34816
	ds_write_b128 v4, v[38:41] offset:34832
	ds_write_b128 v204, v[62:65] offset:17408
	ds_write_b128 v204, v[66:69] offset:17424
	ds_write_b128 v216, v[70:73] offset:61440
	ds_write_b128 v217, v[74:77]
	ds_write_b128 v218, v[78:81]
	s_and_saveexec_b64 s[6:7], s[0:1]
	v_lshl_add_u32 v4, v116, 2, s55
	ds_write_b32 v4, v3
	s_or_b64 exec, exec, s[6:7]
	s_cmpk_eq_i32 s50, 0x100
	s_waitcnt lgkmcnt(0)
	s_barrier
	s_cbranch_scc1 .LBB0_2572
	global_load_dwordx4 v[42:45], v[206:207], off
	global_load_dwordx4 v[38:41], v[206:207], off offset:16
	global_load_dwordx4 v[62:65], v[208:209], off
	global_load_dwordx4 v[66:69], v[208:209], off offset:16
	global_load_dwordx4 v[78:81], v[210:211], off nt
	global_load_dwordx4 v[70:73], v[212:213], off
	global_load_dwordx4 v[74:77], v[214:215], off
	s_and_saveexec_b64 s[6:7], s[0:1]
	global_load_dword v3, v[106:107], off
	s_or_b64 exec, exec, s[6:7]
	v_lshl_add_u64 v[206:207], v[206:207], 0, s[36:37]
	v_lshl_add_u64 v[208:209], v[208:209], 0, s[36:37]
	v_lshl_add_u64 v[210:211], v[210:211], 0, s[36:37]
	v_lshl_add_u64 v[212:213], v[212:213], 0, s[36:37]
	v_lshl_add_u64 v[214:215], v[214:215], 0, s[36:37]
